# norm pass rows mapped XCD-locally (rows of the 16 panels an XCD owns in the GEMMs are normalised by that XCD)
# speedup vs baseline: 1.0004x; 1.0004x over previous
.LBB0_451:
	s_andn2_b64 vcc, exec, s[0:1]
	s_cbranch_vccnz .LBB0_457
	s_cmp_gt_i32 s20, 0x81ff
	s_cbranch_scc1 .LBB0_457
	s_waitcnt lgkmcnt(0)
	v_readlane_b32 s0, v255, 12
	v_readlane_b32 s1, v255, 13
	v_readlane_b32 s34, v251, 49
	v_readlane_b32 s35, v251, 50
	v_lshlrev_b32_e32 v130, 4, v189
	v_lshlrev_b32_e32 v131, 3, v189
	s_nop 1
	global_load_dwordx4 v[48:51], v130, s[0:1]
	global_load_dwordx4 v[52:55], v130, s[0:1] offset:1024
	global_load_dwordx4 v[56:59], v130, s[0:1] offset:2048
	global_load_dwordx4 v[60:63], v130, s[0:1] offset:3072
	s_mov_b32 s11, s20
	s_movk_i32 s27, 0x800
	s_cmp_eq_u32 s4, s27
	s_mov_b32 s26, 0x8000
	s_mov_b32 s27, s4
	s_cbranch_scc0 .Lnrm_map_done
	s_and_b32 s2, s59, 7
	s_lshl_b32 s2, s2, 12
	s_lshr_b32 s3, s59, 3
	s_lshl_b32 s3, s3, 3
	s_and_b32 s10, s20, 7
	s_add_u32 s3, s3, s10
	s_add_u32 s20, s2, s3
	s_add_u32 s26, s2, 0x1000
	s_movk_i32 s27, 0x100
.Lnrm_map_done:
	s_cmp_lt_u32 s20, s26
	s_cbranch_scc0 .Lnrm_special
	s_lshl_b32 s2, s20, 12
	v_add_u32_e32 v132, s2, v130
	global_load_dwordx4 v[0:3], v132, s[72:73] nt
	global_load_dwordx4 v[4:7], v132, s[72:73] offset:1024 nt
	global_load_dwordx4 v[8:11], v132, s[72:73] offset:2048 nt
	global_load_dwordx4 v[12:15], v132, s[72:73] offset:3072 nt
	s_add_u32 s21, s20, s27
	s_cmp_lt_u32 s21, s26
	s_cselect_b32 s2, s21, s20
	s_lshl_b32 s2, s2, 12
	s_add_u32 s21, s21, s27
	v_add_u32_e32 v132, s2, v130
	global_load_dwordx4 v[16:19], v132, s[72:73] nt
	global_load_dwordx4 v[20:23], v132, s[72:73] offset:1024 nt
	global_load_dwordx4 v[24:27], v132, s[72:73] offset:2048 nt
	global_load_dwordx4 v[28:31], v132, s[72:73] offset:3072 nt
	s_cmp_lt_u32 s21, s26
	s_cselect_b32 s2, s21, s20
	s_lshl_b32 s2, s2, 12
	s_add_u32 s21, s21, s27
	v_add_u32_e32 v132, s2, v130
	global_load_dwordx4 v[32:35], v132, s[72:73] nt
	global_load_dwordx4 v[36:39], v132, s[72:73] offset:1024 nt
	global_load_dwordx4 v[40:43], v132, s[72:73] offset:2048 nt
	global_load_dwordx4 v[44:47], v132, s[72:73] offset:3072 nt
	s_waitcnt vmcnt(8)
	v_mul_f32_e32 v146, v0, v0
	v_mul_f32_e32 v147, v4, v4
	v_mul_f32_e32 v148, v8, v8
	v_mul_f32_e32 v149, v12, v12
	v_fmac_f32_e32 v146, v1, v1
	v_fmac_f32_e32 v147, v5, v5
	v_fmac_f32_e32 v148, v9, v9
	v_fmac_f32_e32 v149, v13, v13
	v_mul_f32_e32 v138, v2, v2
	v_mul_f32_e32 v139, v6, v6
	v_mul_f32_e32 v140, v10, v10
	v_mul_f32_e32 v141, v14, v14
	v_fmac_f32_e32 v138, v3, v3
	v_fmac_f32_e32 v139, v7, v7
	v_fmac_f32_e32 v140, v11, v11
	v_fmac_f32_e32 v141, v15, v15
	v_add_f32_e32 v146, v146, v138
	v_add_f32_e32 v147, v147, v139
	v_add_f32_e32 v148, v148, v140
	v_add_f32_e32 v149, v149, v141
	v_add_f32_e32 v134, v146, v147
	v_add_f32_e32 v134, v134, v148
	v_add_f32_e32 v134, v134, v149
	s_lshl_b32 s3, s20, 11
	s_nop 0
	v_add_f32_dpp v134, v134, v134 quad_perm:[1,0,3,2] row_mask:0xf bank_mask:0xf
	s_nop 1
	v_add_f32_dpp v134, v134, v134 quad_perm:[2,3,0,1] row_mask:0xf bank_mask:0xf
	s_nop 1
	v_add_f32_dpp v134, v134, v134 row_half_mirror row_mask:0xf bank_mask:0xf
	s_nop 1
	v_add_f32_dpp v134, v134, v134 row_mirror row_mask:0xf bank_mask:0xf
	s_nop 1
	v_add_f32_dpp v134, v134, v134 row_bcast:15 row_mask:0xa bank_mask:0xf
	s_nop 1
	v_add_f32_dpp v134, v134, v134 row_bcast:31 row_mask:0xc bank_mask:0xf
	s_nop 1
	v_readlane_b32 s10, v134, 63
	v_add_u32_e32 v133, s3, v131
	s_nop 1
	v_mov_b32_e32 v136, s10
	v_fmamk_f32 v136, v136, 0x3a800000, v172
	v_rsq_f32_e32 v136, v136
	s_nop 0
	v_pk_mul_f32 v[0:1], v[0:1], v[136:137] op_sel_hi:[1,0]
	v_pk_mul_f32 v[2:3], v[2:3], v[136:137] op_sel_hi:[1,0]
	v_pk_mul_f32 v[4:5], v[4:5], v[136:137] op_sel_hi:[1,0]
	v_pk_mul_f32 v[6:7], v[6:7], v[136:137] op_sel_hi:[1,0]
	v_pk_mul_f32 v[8:9], v[8:9], v[136:137] op_sel_hi:[1,0]
	v_pk_mul_f32 v[10:11], v[10:11], v[136:137] op_sel_hi:[1,0]
	v_pk_mul_f32 v[12:13], v[12:13], v[136:137] op_sel_hi:[1,0]
	v_pk_mul_f32 v[14:15], v[14:15], v[136:137] op_sel_hi:[1,0]
	v_pk_mul_f32 v[0:1], v[0:1], v[48:49]
	v_pk_mul_f32 v[2:3], v[2:3], v[50:51]
	v_pk_mul_f32 v[4:5], v[4:5], v[52:53]
	v_pk_mul_f32 v[6:7], v[6:7], v[54:55]
	v_pk_mul_f32 v[8:9], v[8:9], v[56:57]
	v_pk_mul_f32 v[10:11], v[10:11], v[58:59]
	v_pk_mul_f32 v[12:13], v[12:13], v[60:61]
	v_pk_mul_f32 v[14:15], v[14:15], v[62:63]
	v_cvt_pk_bf16_f32 v138, v0, v1
	v_cvt_pk_bf16_f32 v139, v2, v3
	v_cvt_pk_bf16_f32 v140, v4, v5
	v_cvt_pk_bf16_f32 v141, v6, v7
	v_cvt_pk_bf16_f32 v142, v8, v9
	v_cvt_pk_bf16_f32 v143, v10, v11
	v_cvt_pk_bf16_f32 v144, v12, v13
	v_cvt_pk_bf16_f32 v145, v14, v15
	global_store_dwordx2 v133, v[138:139], s[68:69]
	global_store_dwordx2 v133, v[140:141], s[68:69] offset:512
	global_store_dwordx2 v133, v[142:143], s[68:69] offset:1024
	global_store_dwordx2 v133, v[144:145], s[68:69] offset:1536
	s_cmp_lt_u32 s21, s26
	s_cselect_b32 s2, s21, s20
	s_lshl_b32 s2, s2, 12
	s_add_u32 s21, s21, s27
	v_add_u32_e32 v132, s2, v130
	global_load_dwordx4 v[0:3], v132, s[72:73] nt
	global_load_dwordx4 v[4:7], v132, s[72:73] offset:1024 nt
	global_load_dwordx4 v[8:11], v132, s[72:73] offset:2048 nt
	global_load_dwordx4 v[12:15], v132, s[72:73] offset:3072 nt
	s_add_u32 s20, s20, s27
	s_cmp_lt_u32 s20, s26
	s_cbranch_scc0 .Lnrm_special
	s_waitcnt vmcnt(12)
	v_mul_f32_e32 v146, v16, v16
	v_mul_f32_e32 v147, v20, v20
	v_mul_f32_e32 v148, v24, v24
	v_mul_f32_e32 v149, v28, v28
	v_fmac_f32_e32 v146, v17, v17
	v_fmac_f32_e32 v147, v21, v21
	v_fmac_f32_e32 v148, v25, v25
	v_fmac_f32_e32 v149, v29, v29
	v_mul_f32_e32 v138, v18, v18
	v_mul_f32_e32 v139, v22, v22
	v_mul_f32_e32 v140, v26, v26
	v_mul_f32_e32 v141, v30, v30
	v_fmac_f32_e32 v138, v19, v19
	v_fmac_f32_e32 v139, v23, v23
	v_fmac_f32_e32 v140, v27, v27
	v_fmac_f32_e32 v141, v31, v31
	v_add_f32_e32 v146, v146, v138
	v_add_f32_e32 v147, v147, v139
	v_add_f32_e32 v148, v148, v140
	v_add_f32_e32 v149, v149, v141
	v_add_f32_e32 v134, v146, v147
	v_add_f32_e32 v134, v134, v148
	v_add_f32_e32 v134, v134, v149
	s_lshl_b32 s3, s20, 11
	s_nop 0
	v_add_f32_dpp v134, v134, v134 quad_perm:[1,0,3,2] row_mask:0xf bank_mask:0xf
	s_nop 1
	v_add_f32_dpp v134, v134, v134 quad_perm:[2,3,0,1] row_mask:0xf bank_mask:0xf
	s_nop 1
	v_add_f32_dpp v134, v134, v134 row_half_mirror row_mask:0xf bank_mask:0xf
	s_nop 1
	v_add_f32_dpp v134, v134, v134 row_mirror row_mask:0xf bank_mask:0xf
	s_nop 1
	v_add_f32_dpp v134, v134, v134 row_bcast:15 row_mask:0xa bank_mask:0xf
	s_nop 1
	v_add_f32_dpp v134, v134, v134 row_bcast:31 row_mask:0xc bank_mask:0xf
	s_nop 1
	v_readlane_b32 s10, v134, 63
	v_add_u32_e32 v133, s3, v131
	s_nop 1
	v_mov_b32_e32 v136, s10
	v_fmamk_f32 v136, v136, 0x3a800000, v172
	v_rsq_f32_e32 v136, v136
	s_nop 0
	v_pk_mul_f32 v[16:17], v[16:17], v[136:137] op_sel_hi:[1,0]
	v_pk_mul_f32 v[18:19], v[18:19], v[136:137] op_sel_hi:[1,0]
	v_pk_mul_f32 v[20:21], v[20:21], v[136:137] op_sel_hi:[1,0]
	v_pk_mul_f32 v[22:23], v[22:23], v[136:137] op_sel_hi:[1,0]
	v_pk_mul_f32 v[24:25], v[24:25], v[136:137] op_sel_hi:[1,0]
	v_pk_mul_f32 v[26:27], v[26:27], v[136:137] op_sel_hi:[1,0]
	v_pk_mul_f32 v[28:29], v[28:29], v[136:137] op_sel_hi:[1,0]
	v_pk_mul_f32 v[30:31], v[30:31], v[136:137] op_sel_hi:[1,0]
	v_pk_mul_f32 v[16:17], v[16:17], v[48:49]
	v_pk_mul_f32 v[18:19], v[18:19], v[50:51]
	v_pk_mul_f32 v[20:21], v[20:21], v[52:53]
	v_pk_mul_f32 v[22:23], v[22:23], v[54:55]
	v_pk_mul_f32 v[24:25], v[24:25], v[56:57]
	v_pk_mul_f32 v[26:27], v[26:27], v[58:59]
	v_pk_mul_f32 v[28:29], v[28:29], v[60:61]
	v_pk_mul_f32 v[30:31], v[30:31], v[62:63]
	v_cvt_pk_bf16_f32 v138, v16, v17
	v_cvt_pk_bf16_f32 v139, v18, v19
	v_cvt_pk_bf16_f32 v140, v20, v21
	v_cvt_pk_bf16_f32 v141, v22, v23
	v_cvt_pk_bf16_f32 v142, v24, v25
	v_cvt_pk_bf16_f32 v143, v26, v27
	v_cvt_pk_bf16_f32 v144, v28, v29
	v_cvt_pk_bf16_f32 v145, v30, v31
	global_store_dwordx2 v133, v[138:139], s[68:69]
	global_store_dwordx2 v133, v[140:141], s[68:69] offset:512
	global_store_dwordx2 v133, v[142:143], s[68:69] offset:1024
	global_store_dwordx2 v133, v[144:145], s[68:69] offset:1536
	s_cmp_lt_u32 s21, s26
	s_cselect_b32 s2, s21, s20
	s_lshl_b32 s2, s2, 12
	s_add_u32 s21, s21, s27
	v_add_u32_e32 v132, s2, v130
	global_load_dwordx4 v[16:19], v132, s[72:73] nt
	global_load_dwordx4 v[20:23], v132, s[72:73] offset:1024 nt
	global_load_dwordx4 v[24:27], v132, s[72:73] offset:2048 nt
	global_load_dwordx4 v[28:31], v132, s[72:73] offset:3072 nt
	s_add_u32 s20, s20, s27
	s_cmp_lt_u32 s20, s26
	s_cbranch_scc0 .Lnrm_special
.Lnrm_loop:
	s_waitcnt vmcnt(16)
	v_mul_f32_e32 v146, v32, v32
	v_mul_f32_e32 v147, v36, v36
	v_mul_f32_e32 v148, v40, v40
	v_mul_f32_e32 v149, v44, v44
	v_fmac_f32_e32 v146, v33, v33
	v_fmac_f32_e32 v147, v37, v37
	v_fmac_f32_e32 v148, v41, v41
	v_fmac_f32_e32 v149, v45, v45
	v_mul_f32_e32 v138, v34, v34
	v_mul_f32_e32 v139, v38, v38
	v_mul_f32_e32 v140, v42, v42
	v_mul_f32_e32 v141, v46, v46
	v_fmac_f32_e32 v138, v35, v35
	v_fmac_f32_e32 v139, v39, v39
	v_fmac_f32_e32 v140, v43, v43
	v_fmac_f32_e32 v141, v47, v47
	v_add_f32_e32 v146, v146, v138
	v_add_f32_e32 v147, v147, v139
	v_add_f32_e32 v148, v148, v140
	v_add_f32_e32 v149, v149, v141
	v_add_f32_e32 v134, v146, v147
	v_add_f32_e32 v134, v134, v148
	v_add_f32_e32 v134, v134, v149
	s_lshl_b32 s3, s20, 11
	s_nop 0
	v_add_f32_dpp v134, v134, v134 quad_perm:[1,0,3,2] row_mask:0xf bank_mask:0xf
	s_nop 1
	v_add_f32_dpp v134, v134, v134 quad_perm:[2,3,0,1] row_mask:0xf bank_mask:0xf
	s_nop 1
	v_add_f32_dpp v134, v134, v134 row_half_mirror row_mask:0xf bank_mask:0xf
	s_nop 1
	v_add_f32_dpp v134, v134, v134 row_mirror row_mask:0xf bank_mask:0xf
	s_nop 1
	v_add_f32_dpp v134, v134, v134 row_bcast:15 row_mask:0xa bank_mask:0xf
	s_nop 1
	v_add_f32_dpp v134, v134, v134 row_bcast:31 row_mask:0xc bank_mask:0xf
	s_nop 1
	v_readlane_b32 s10, v134, 63
	v_add_u32_e32 v133, s3, v131
	s_nop 1
	v_mov_b32_e32 v136, s10
	v_fmamk_f32 v136, v136, 0x3a800000, v172
	v_rsq_f32_e32 v136, v136
	s_nop 0
	v_pk_mul_f32 v[32:33], v[32:33], v[136:137] op_sel_hi:[1,0]
	v_pk_mul_f32 v[34:35], v[34:35], v[136:137] op_sel_hi:[1,0]
	v_pk_mul_f32 v[36:37], v[36:37], v[136:137] op_sel_hi:[1,0]
	v_pk_mul_f32 v[38:39], v[38:39], v[136:137] op_sel_hi:[1,0]
	v_pk_mul_f32 v[40:41], v[40:41], v[136:137] op_sel_hi:[1,0]
	v_pk_mul_f32 v[42:43], v[42:43], v[136:137] op_sel_hi:[1,0]
	v_pk_mul_f32 v[44:45], v[44:45], v[136:137] op_sel_hi:[1,0]
	v_pk_mul_f32 v[46:47], v[46:47], v[136:137] op_sel_hi:[1,0]
	v_pk_mul_f32 v[32:33], v[32:33], v[48:49]
	v_pk_mul_f32 v[34:35], v[34:35], v[50:51]
	v_pk_mul_f32 v[36:37], v[36:37], v[52:53]
	v_pk_mul_f32 v[38:39], v[38:39], v[54:55]
	v_pk_mul_f32 v[40:41], v[40:41], v[56:57]
	v_pk_mul_f32 v[42:43], v[42:43], v[58:59]
	v_pk_mul_f32 v[44:45], v[44:45], v[60:61]
	v_pk_mul_f32 v[46:47], v[46:47], v[62:63]
	v_cvt_pk_bf16_f32 v138, v32, v33
	v_cvt_pk_bf16_f32 v139, v34, v35
	v_cvt_pk_bf16_f32 v140, v36, v37
	v_cvt_pk_bf16_f32 v141, v38, v39
	v_cvt_pk_bf16_f32 v142, v40, v41
	v_cvt_pk_bf16_f32 v143, v42, v43
	v_cvt_pk_bf16_f32 v144, v44, v45
	v_cvt_pk_bf16_f32 v145, v46, v47
	global_store_dwordx2 v133, v[138:139], s[68:69]
	global_store_dwordx2 v133, v[140:141], s[68:69] offset:512
	global_store_dwordx2 v133, v[142:143], s[68:69] offset:1024
	global_store_dwordx2 v133, v[144:145], s[68:69] offset:1536
	s_cmp_lt_u32 s21, s26
	s_cselect_b32 s2, s21, s20
	s_lshl_b32 s2, s2, 12
	s_add_u32 s21, s21, s27
	v_add_u32_e32 v132, s2, v130
	global_load_dwordx4 v[32:35], v132, s[72:73] nt
	global_load_dwordx4 v[36:39], v132, s[72:73] offset:1024 nt
	global_load_dwordx4 v[40:43], v132, s[72:73] offset:2048 nt
	global_load_dwordx4 v[44:47], v132, s[72:73] offset:3072 nt
	s_add_u32 s20, s20, s27
	s_cmp_lt_u32 s20, s26
	s_cbranch_scc0 .Lnrm_special
	s_waitcnt vmcnt(16)
	v_mul_f32_e32 v146, v0, v0
	v_mul_f32_e32 v147, v4, v4
	v_mul_f32_e32 v148, v8, v8
	v_mul_f32_e32 v149, v12, v12
	v_fmac_f32_e32 v146, v1, v1
	v_fmac_f32_e32 v147, v5, v5
	v_fmac_f32_e32 v148, v9, v9
	v_fmac_f32_e32 v149, v13, v13
	v_mul_f32_e32 v138, v2, v2
	v_mul_f32_e32 v139, v6, v6
	v_mul_f32_e32 v140, v10, v10
	v_mul_f32_e32 v141, v14, v14
	v_fmac_f32_e32 v138, v3, v3
	v_fmac_f32_e32 v139, v7, v7
	v_fmac_f32_e32 v140, v11, v11
	v_fmac_f32_e32 v141, v15, v15
	v_add_f32_e32 v146, v146, v138
	v_add_f32_e32 v147, v147, v139
	v_add_f32_e32 v148, v148, v140
	v_add_f32_e32 v149, v149, v141
	v_add_f32_e32 v134, v146, v147
	v_add_f32_e32 v134, v134, v148
	v_add_f32_e32 v134, v134, v149
	s_lshl_b32 s3, s20, 11
	s_nop 0
	v_add_f32_dpp v134, v134, v134 quad_perm:[1,0,3,2] row_mask:0xf bank_mask:0xf
	s_nop 1
	v_add_f32_dpp v134, v134, v134 quad_perm:[2,3,0,1] row_mask:0xf bank_mask:0xf
	s_nop 1
	v_add_f32_dpp v134, v134, v134 row_half_mirror row_mask:0xf bank_mask:0xf
	s_nop 1
	v_add_f32_dpp v134, v134, v134 row_mirror row_mask:0xf bank_mask:0xf
	s_nop 1
	v_add_f32_dpp v134, v134, v134 row_bcast:15 row_mask:0xa bank_mask:0xf
	s_nop 1
	v_add_f32_dpp v134, v134, v134 row_bcast:31 row_mask:0xc bank_mask:0xf
	s_nop 1
	v_readlane_b32 s10, v134, 63
	v_add_u32_e32 v133, s3, v131
	s_nop 1
	v_mov_b32_e32 v136, s10
	v_fmamk_f32 v136, v136, 0x3a800000, v172
	v_rsq_f32_e32 v136, v136
	s_nop 0
	v_pk_mul_f32 v[0:1], v[0:1], v[136:137] op_sel_hi:[1,0]
	v_pk_mul_f32 v[2:3], v[2:3], v[136:137] op_sel_hi:[1,0]
	v_pk_mul_f32 v[4:5], v[4:5], v[136:137] op_sel_hi:[1,0]
	v_pk_mul_f32 v[6:7], v[6:7], v[136:137] op_sel_hi:[1,0]
	v_pk_mul_f32 v[8:9], v[8:9], v[136:137] op_sel_hi:[1,0]
	v_pk_mul_f32 v[10:11], v[10:11], v[136:137] op_sel_hi:[1,0]
	v_pk_mul_f32 v[12:13], v[12:13], v[136:137] op_sel_hi:[1,0]
	v_pk_mul_f32 v[14:15], v[14:15], v[136:137] op_sel_hi:[1,0]
	v_pk_mul_f32 v[0:1], v[0:1], v[48:49]
	v_pk_mul_f32 v[2:3], v[2:3], v[50:51]
	v_pk_mul_f32 v[4:5], v[4:5], v[52:53]
	v_pk_mul_f32 v[6:7], v[6:7], v[54:55]
	v_pk_mul_f32 v[8:9], v[8:9], v[56:57]
	v_pk_mul_f32 v[10:11], v[10:11], v[58:59]
	v_pk_mul_f32 v[12:13], v[12:13], v[60:61]
	v_pk_mul_f32 v[14:15], v[14:15], v[62:63]
	v_cvt_pk_bf16_f32 v138, v0, v1
	v_cvt_pk_bf16_f32 v139, v2, v3
	v_cvt_pk_bf16_f32 v140, v4, v5
	v_cvt_pk_bf16_f32 v141, v6, v7
	v_cvt_pk_bf16_f32 v142, v8, v9
	v_cvt_pk_bf16_f32 v143, v10, v11
	v_cvt_pk_bf16_f32 v144, v12, v13
	v_cvt_pk_bf16_f32 v145, v14, v15
	global_store_dwordx2 v133, v[138:139], s[68:69]
	global_store_dwordx2 v133, v[140:141], s[68:69] offset:512
	global_store_dwordx2 v133, v[142:143], s[68:69] offset:1024
	global_store_dwordx2 v133, v[144:145], s[68:69] offset:1536
	s_cmp_lt_u32 s21, s26
	s_cselect_b32 s2, s21, s20
	s_lshl_b32 s2, s2, 12
	s_add_u32 s21, s21, s27
	v_add_u32_e32 v132, s2, v130
	global_load_dwordx4 v[0:3], v132, s[72:73] nt
	global_load_dwordx4 v[4:7], v132, s[72:73] offset:1024 nt
	global_load_dwordx4 v[8:11], v132, s[72:73] offset:2048 nt
	global_load_dwordx4 v[12:15], v132, s[72:73] offset:3072 nt
	s_add_u32 s20, s20, s27
	s_cmp_lt_u32 s20, s26
	s_cbranch_scc0 .Lnrm_special
	s_waitcnt vmcnt(16)
	v_mul_f32_e32 v146, v16, v16
	v_mul_f32_e32 v147, v20, v20
	v_mul_f32_e32 v148, v24, v24
	v_mul_f32_e32 v149, v28, v28
	v_fmac_f32_e32 v146, v17, v17
	v_fmac_f32_e32 v147, v21, v21
	v_fmac_f32_e32 v148, v25, v25
	v_fmac_f32_e32 v149, v29, v29
	v_mul_f32_e32 v138, v18, v18
	v_mul_f32_e32 v139, v22, v22
	v_mul_f32_e32 v140, v26, v26
	v_mul_f32_e32 v141, v30, v30
	v_fmac_f32_e32 v138, v19, v19
	v_fmac_f32_e32 v139, v23, v23
	v_fmac_f32_e32 v140, v27, v27
	v_fmac_f32_e32 v141, v31, v31
	v_add_f32_e32 v146, v146, v138
	v_add_f32_e32 v147, v147, v139
	v_add_f32_e32 v148, v148, v140
	v_add_f32_e32 v149, v149, v141
	v_add_f32_e32 v134, v146, v147
	v_add_f32_e32 v134, v134, v148
	v_add_f32_e32 v134, v134, v149
	s_lshl_b32 s3, s20, 11
	s_nop 0
	v_add_f32_dpp v134, v134, v134 quad_perm:[1,0,3,2] row_mask:0xf bank_mask:0xf
	s_nop 1
	v_add_f32_dpp v134, v134, v134 quad_perm:[2,3,0,1] row_mask:0xf bank_mask:0xf
	s_nop 1
	v_add_f32_dpp v134, v134, v134 row_half_mirror row_mask:0xf bank_mask:0xf
	s_nop 1
	v_add_f32_dpp v134, v134, v134 row_mirror row_mask:0xf bank_mask:0xf
	s_nop 1
	v_add_f32_dpp v134, v134, v134 row_bcast:15 row_mask:0xa bank_mask:0xf
	s_nop 1
	v_add_f32_dpp v134, v134, v134 row_bcast:31 row_mask:0xc bank_mask:0xf
	s_nop 1
	v_readlane_b32 s10, v134, 63
	v_add_u32_e32 v133, s3, v131
	s_nop 1
	v_mov_b32_e32 v136, s10
	v_fmamk_f32 v136, v136, 0x3a800000, v172
	v_rsq_f32_e32 v136, v136
	s_nop 0
	v_pk_mul_f32 v[16:17], v[16:17], v[136:137] op_sel_hi:[1,0]
	v_pk_mul_f32 v[18:19], v[18:19], v[136:137] op_sel_hi:[1,0]
	v_pk_mul_f32 v[20:21], v[20:21], v[136:137] op_sel_hi:[1,0]
	v_pk_mul_f32 v[22:23], v[22:23], v[136:137] op_sel_hi:[1,0]
	v_pk_mul_f32 v[24:25], v[24:25], v[136:137] op_sel_hi:[1,0]
	v_pk_mul_f32 v[26:27], v[26:27], v[136:137] op_sel_hi:[1,0]
	v_pk_mul_f32 v[28:29], v[28:29], v[136:137] op_sel_hi:[1,0]
	v_pk_mul_f32 v[30:31], v[30:31], v[136:137] op_sel_hi:[1,0]
	v_pk_mul_f32 v[16:17], v[16:17], v[48:49]
	v_pk_mul_f32 v[18:19], v[18:19], v[50:51]
	v_pk_mul_f32 v[20:21], v[20:21], v[52:53]
	v_pk_mul_f32 v[22:23], v[22:23], v[54:55]
	v_pk_mul_f32 v[24:25], v[24:25], v[56:57]
	v_pk_mul_f32 v[26:27], v[26:27], v[58:59]
	v_pk_mul_f32 v[28:29], v[28:29], v[60:61]
	v_pk_mul_f32 v[30:31], v[30:31], v[62:63]
	v_cvt_pk_bf16_f32 v138, v16, v17
	v_cvt_pk_bf16_f32 v139, v18, v19
	v_cvt_pk_bf16_f32 v140, v20, v21
	v_cvt_pk_bf16_f32 v141, v22, v23
	v_cvt_pk_bf16_f32 v142, v24, v25
	v_cvt_pk_bf16_f32 v143, v26, v27
	v_cvt_pk_bf16_f32 v144, v28, v29
	v_cvt_pk_bf16_f32 v145, v30, v31
	global_store_dwordx2 v133, v[138:139], s[68:69]
	global_store_dwordx2 v133, v[140:141], s[68:69] offset:512
	global_store_dwordx2 v133, v[142:143], s[68:69] offset:1024
	global_store_dwordx2 v133, v[144:145], s[68:69] offset:1536
	s_cmp_lt_u32 s21, s26
	s_cselect_b32 s2, s21, s20
	s_lshl_b32 s2, s2, 12
	s_add_u32 s21, s21, s27
	v_add_u32_e32 v132, s2, v130
	global_load_dwordx4 v[16:19], v132, s[72:73] nt
	global_load_dwordx4 v[20:23], v132, s[72:73] offset:1024 nt
	global_load_dwordx4 v[24:27], v132, s[72:73] offset:2048 nt
	global_load_dwordx4 v[28:31], v132, s[72:73] offset:3072 nt
	s_add_u32 s20, s20, s27
	s_cmp_lt_u32 s20, s26
	s_cbranch_scc0 .Lnrm_special
	s_branch .Lnrm_loop
.Lnrm_special:
	s_waitcnt vmcnt(0)
	s_cmp_eq_u32 s27, s4
	s_cbranch_scc1 .Lnrm_sp_chk
	s_add_u32 s20, s11, 0x8000
.Lnrm_sp_chk:
	s_cmp_gt_i32 s20, 0x81ff
	s_cbranch_scc1 .Lnrm_done
